# sample in-proj: all weight fragments of a task requested up front (on top of slab-order rotation and out-proj K rotation)
# speedup vs baseline: 1.0500x; 1.0033x over previous
.LBB0_607:
	s_ashr_i32 s8, s0, 8
	s_mul_i32 s7, s6, 24
	s_lshl_b32 s12, s8, 14
	v_and_b32_e32 v17, 63, v16
	s_sub_i32 s7, s1, s7
	s_bfe_u32 s1, s0, 0x20006
	s_lshl_b32 s9, s8, 4
	s_add_i32 s12, s12, 0
	v_lshlrev_b32_e32 v196, 4, v17
	s_add_u32 s16, s10, s89
	v_add_u32_e32 v154, s12, v196
	s_addc_u32 s17, s11, s22
	s_lshl_b32 s12, s7, 8
	s_lshl_b32 s13, s1, 5
	s_add_i32 s9, s9, s12
	s_add_i32 s12, s9, s13
	s_ashr_i32 s13, s12, 31
	s_lshl_b64 s[12:13], s[12:13], 10
	s_add_u32 s12, s16, s12
	s_addc_u32 s13, s17, s13
	v_lshl_add_u64 v[0:1], s[12:13], 0, v[196:197]
	s_mov_b32 s9, 0x12002000
	v_add_co_u32_e32 v126, vcc, s9, v0
	s_mov_b32 s9, 0x12021000
	s_nop 0
	v_addc_co_u32_e32 v127, vcc, 0, v1, vcc
	v_add_co_u32_e32 v66, vcc, s9, v0
	s_mov_b32 s9, 0x12022000
	s_nop 0
	v_addc_co_u32_e32 v67, vcc, 0, v1, vcc
	s_mov_b64 s[12:13], 0x12001000
	v_add_co_u32_e32 v130, vcc, s9, v0
	v_lshl_add_u64 v[14:15], v[0:1], 0, s[12:13]
	s_nop 0
	v_addc_co_u32_e32 v131, vcc, 0, v1, vcc
	v_add_u32_e32 v155, 0x8000, v154
	ds_read_b128 v[2:5], v154 offset:32768
	ds_read_b128 v[6:9], v155 offset:32768
	global_load_dwordx4 v[10:13], v[126:127], off offset:-4096
	global_load_dwordx4 v[18:21], v[130:131], off offset:-4096
	ds_read_b128 v[22:25], v154 offset:33792
	ds_read_b128 v[26:29], v155 offset:33792
	global_load_dwordx4 v[30:33], v[14:15], off offset:1024
	global_load_dwordx4 v[34:37], v[66:67], off offset:1024
	ds_read_b128 v[38:41], v154 offset:34816
	ds_read_b128 v[42:45], v155 offset:34816
	global_load_dwordx4 v[46:49], v[14:15], off offset:2048
	global_load_dwordx4 v[50:53], v[66:67], off offset:2048
	ds_read_b128 v[54:57], v154 offset:35840
	ds_read_b128 v[58:61], v155 offset:35840
	global_load_dwordx4 v[62:65], v[14:15], off offset:3072
	s_nop 0
	global_load_dwordx4 v[66:69], v[66:67], off offset:3072
	ds_read_b128 v[70:73], v154 offset:36864
	ds_read_b128 v[74:77], v155 offset:36864
	global_load_dwordx4 v[78:81], v[126:127], off
	global_load_dwordx4 v[82:85], v[130:131], off
	ds_read_b128 v[86:89], v154 offset:37888
	ds_read_b128 v[90:93], v155 offset:37888
	global_load_dwordx4 v[94:97], v[126:127], off offset:1024
	global_load_dwordx4 v[98:101], v[130:131], off offset:1024
	ds_read_b128 v[102:105], v154 offset:38912
	ds_read_b128 v[106:109], v155 offset:38912
	global_load_dwordx4 v[110:113], v[126:127], off offset:2048
	global_load_dwordx4 v[114:117], v[130:131], off offset:2048
	ds_read_b128 v[118:121], v154 offset:39936
	ds_read_b128 v[122:125], v155 offset:39936
	global_load_dwordx4 v[126:129], v[126:127], off offset:3072
	s_nop 0
	global_load_dwordx4 v[130:133], v[130:131], off offset:3072
	s_mov_b64 s[44:45], 0x12003000
	s_mov_b64 s[46:47], 0x12023000
	s_mov_b64 s[48:49], 0x12024000
	s_mov_b64 s[50:51], 0x12004000
	v_lshl_add_u64 v[246:247], v[0:1], 0, s[44:45]
	v_lshl_add_u64 v[248:249], v[0:1], 0, s[46:47]
	v_lshl_add_u64 v[250:251], v[0:1], 0, s[48:49]
	v_lshl_add_u64 v[252:253], v[0:1], 0, s[50:51]
	global_load_dwordx4 v[156:159], v[246:247], off offset:3072
	global_load_dwordx4 v[160:163], v[246:247], off offset:2048
	global_load_dwordx4 v[164:167], v[248:249], off offset:2048
	global_load_dwordx4 v[168:171], v[248:249], off offset:1024
	global_load_dwordx4 v[172:175], v[248:249], off offset:3072
	global_load_dwordx4 v[176:179], v[246:247], off offset:1024
	global_load_dwordx4 v[180:183], v[250:251], off offset:-4096
	global_load_dwordx4 v[184:187], v[252:253], off offset:-4096
	global_load_dwordx4 v[188:191], v[252:253], off
	global_load_dwordx4 v[202:205], v[252:253], off offset:1024
	global_load_dwordx4 v[206:209], v[250:251], off
	global_load_dwordx4 v[210:213], v[250:251], off offset:1024
	global_load_dwordx4 v[214:217], v[252:253], off offset:2048
	global_load_dwordx4 v[218:221], v[252:253], off offset:3072
	global_load_dwordx4 v[238:241], v[250:251], off offset:2048
	global_load_dwordx4 v[242:245], v[250:251], off offset:3072
	s_waitcnt vmcnt(24) lgkmcnt(0)
	v_mfma_f32_16x16x32_bf16 v[134:137], v[10:13], v[2:5], 0
	v_mfma_f32_16x16x32_bf16 v[2:5], v[18:21], v[2:5], 0
	v_mfma_f32_16x16x32_bf16 v[10:13], v[10:13], v[6:9], 0
	v_mfma_f32_16x16x32_bf16 v[6:9], v[18:21], v[6:9], 0
	v_mfma_f32_16x16x32_bf16 v[2:5], v[34:37], v[22:25], v[2:5]
	v_mfma_f32_16x16x32_bf16 v[10:13], v[30:33], v[26:29], v[10:13]
	v_mfma_f32_16x16x32_bf16 v[6:9], v[34:37], v[26:29], v[6:9]
	v_mfma_f32_16x16x32_bf16 v[18:21], v[30:33], v[22:25], v[134:137]
	v_mfma_f32_16x16x32_bf16 v[2:5], v[50:53], v[38:41], v[2:5]
	v_mfma_f32_16x16x32_bf16 v[10:13], v[46:49], v[42:45], v[10:13]
	v_mfma_f32_16x16x32_bf16 v[6:9], v[50:53], v[42:45], v[6:9]
	v_mfma_f32_16x16x32_bf16 v[18:21], v[46:49], v[38:41], v[18:21]
	v_mfma_f32_16x16x32_bf16 v[2:5], v[66:69], v[54:57], v[2:5]
	v_mfma_f32_16x16x32_bf16 v[10:13], v[62:65], v[58:61], v[10:13]
	v_mfma_f32_16x16x32_bf16 v[6:9], v[66:69], v[58:61], v[6:9]
	v_mfma_f32_16x16x32_bf16 v[18:21], v[62:65], v[54:57], v[18:21]
	ds_read_b128 v[54:57], v155 offset:44032
	ds_read_b128 v[58:61], v155 offset:43008
	ds_read_b128 v[62:65], v154 offset:44032
	ds_read_b128 v[66:69], v154 offset:43008
	ds_read_b128 v[134:137], v155 offset:41984
	ds_read_b128 v[138:141], v155 offset:40960
	ds_read_b128 v[142:145], v154 offset:41984
	ds_read_b128 v[146:149], v154 offset:40960
	s_waitcnt vmcnt(16)
	v_mfma_f32_16x16x32_bf16 v[18:21], v[78:81], v[70:73], v[18:21]
	v_mfma_f32_16x16x32_bf16 v[0:3], v[82:85], v[70:73], v[2:5]
	v_mfma_f32_16x16x32_bf16 v[10:13], v[78:81], v[74:77], v[10:13]
	v_mfma_f32_16x16x32_bf16 v[4:7], v[82:85], v[74:77], v[6:9]
	v_mfma_f32_16x16x32_bf16 v[18:21], v[94:97], v[86:89], v[18:21]
	v_mfma_f32_16x16x32_bf16 v[0:3], v[98:101], v[86:89], v[0:3]
	v_mfma_f32_16x16x32_bf16 v[8:11], v[94:97], v[90:93], v[10:13]
	v_mfma_f32_16x16x32_bf16 v[4:7], v[98:101], v[90:93], v[4:7]
	v_mfma_f32_16x16x32_bf16 v[12:15], v[110:113], v[102:105], v[18:21]
	v_mfma_f32_16x16x32_bf16 v[0:3], v[114:117], v[102:105], v[0:3]
	v_mfma_f32_16x16x32_bf16 v[8:11], v[110:113], v[106:109], v[8:11]
	v_mfma_f32_16x16x32_bf16 v[4:7], v[114:117], v[106:109], v[4:7]
	v_mfma_f32_16x16x32_bf16 v[12:15], v[126:129], v[118:121], v[12:15]
	v_mfma_f32_16x16x32_bf16 v[0:3], v[130:133], v[118:121], v[0:3]
	v_mfma_f32_16x16x32_bf16 v[8:11], v[126:129], v[122:125], v[8:11]
	v_mfma_f32_16x16x32_bf16 v[4:7], v[130:133], v[122:125], v[4:7]
	ds_read_b128 v[98:101], v154 offset:45056
	ds_read_b128 v[102:105], v154 offset:46080
	ds_read_b128 v[106:109], v155 offset:45056
	ds_read_b128 v[110:113], v155 offset:46080
	ds_read_b128 v[114:117], v154 offset:47104
	ds_read_b128 v[118:121], v154 offset:48128
	ds_read_b128 v[122:125], v155 offset:47104
	ds_read_b128 v[126:129], v155 offset:48128
	s_waitcnt vmcnt(8) lgkmcnt(8)
	v_mfma_f32_16x16x32_bf16 v[12:15], v[184:187], v[146:149], v[12:15]
	v_mfma_f32_16x16x32_bf16 v[0:3], v[180:183], v[146:149], v[0:3]
	v_mfma_f32_16x16x32_bf16 v[8:11], v[184:187], v[138:141], v[8:11]
	v_mfma_f32_16x16x32_bf16 v[4:7], v[180:183], v[138:141], v[4:7]
	v_mfma_f32_16x16x32_bf16 v[12:15], v[176:179], v[142:145], v[12:15]
	v_mfma_f32_16x16x32_bf16 v[0:3], v[168:171], v[142:145], v[0:3]
	v_mfma_f32_16x16x32_bf16 v[8:11], v[176:179], v[134:137], v[8:11]
	v_mfma_f32_16x16x32_bf16 v[4:7], v[168:171], v[134:137], v[4:7]
	v_mfma_f32_16x16x32_bf16 v[12:15], v[160:163], v[66:69], v[12:15]
	v_mfma_f32_16x16x32_bf16 v[0:3], v[164:167], v[66:69], v[0:3]
	v_mfma_f32_16x16x32_bf16 v[8:11], v[160:163], v[58:61], v[8:11]
	v_mfma_f32_16x16x32_bf16 v[4:7], v[164:167], v[58:61], v[4:7]
	v_mfma_f32_16x16x32_bf16 v[12:15], v[156:159], v[62:65], v[12:15]
	v_mfma_f32_16x16x32_bf16 v[0:3], v[172:175], v[62:65], v[0:3]
	v_mfma_f32_16x16x32_bf16 v[8:11], v[156:159], v[54:57], v[8:11]
	v_mfma_f32_16x16x32_bf16 v[4:7], v[172:175], v[54:57], v[4:7]
	s_waitcnt vmcnt(7) lgkmcnt(7)
	v_mfma_f32_16x16x32_bf16 v[12:15], v[188:191], v[98:101], v[12:15]
	s_waitcnt vmcnt(5)
	v_mfma_f32_16x16x32_bf16 v[0:3], v[206:209], v[98:101], v[0:3]
	s_waitcnt lgkmcnt(5)
	v_mfma_f32_16x16x32_bf16 v[8:11], v[188:191], v[106:109], v[8:11]
	v_mfma_f32_16x16x32_bf16 v[4:7], v[206:209], v[106:109], v[4:7]
	v_mfma_f32_16x16x32_bf16 v[12:15], v[202:205], v[102:105], v[12:15]
	s_waitcnt vmcnt(4)
	v_mfma_f32_16x16x32_bf16 v[0:3], v[210:213], v[102:105], v[0:3]
	s_waitcnt lgkmcnt(4)
	v_mfma_f32_16x16x32_bf16 v[8:11], v[202:205], v[110:113], v[8:11]
	v_mfma_f32_16x16x32_bf16 v[4:7], v[210:213], v[110:113], v[4:7]
	s_waitcnt vmcnt(3) lgkmcnt(3)
	v_mfma_f32_16x16x32_bf16 v[12:15], v[214:217], v[114:117], v[12:15]
	s_waitcnt vmcnt(1)
	v_mfma_f32_16x16x32_bf16 v[0:3], v[238:241], v[114:117], v[0:3]
	s_waitcnt lgkmcnt(1)
	v_mfma_f32_16x16x32_bf16 v[18:21], v[214:217], v[122:125], v[8:11]
	v_mfma_f32_16x16x32_bf16 v[22:25], v[238:241], v[122:125], v[4:7]
	v_mfma_f32_16x16x32_bf16 v[8:11], v[218:221], v[118:121], v[12:15]
	s_waitcnt vmcnt(0)
	v_mfma_f32_16x16x32_bf16 v[12:15], v[242:245], v[118:121], v[0:3]
	s_waitcnt lgkmcnt(0)
	v_mfma_f32_16x16x32_bf16 v[4:7], v[218:221], v[126:129], v[18:21]
	v_mfma_f32_16x16x32_bf16 v[0:3], v[242:245], v[126:129], v[22:25]
	s_cmp_lg_u32 s8, 1
	s_cbranch_scc1 .LBB0_609
	s_lshl_b32 s1, s1, 12
	s_add_i32 s1, s1, 0
	v_lshl_add_u32 v18, v17, 4, s1
	ds_write_b128 v18, v[8:11]
	ds_write_b128 v18, v[12:15] offset:1024
	ds_write_b128 v18, v[4:7] offset:2048
	ds_write_b128 v18, v[0:3] offset:3072
